# ssd_passB: dt_raw / dt_bias / A_log loads issued before the conv loop (latency covered by the loop) instead of in the dt section
# speedup vs baseline: 1.0020x; 1.0020x over previous
; __device__ __forceinline__ unsigned f2bf(float f) { return pk2(f, 0.f) & 0xffffu; }
; __device__ __forceinline__ float siluf(float x) { return x * __builtin_amdgcn_rcpf(1.0f + __expf(-x)); }
; __device__ __forceinline__ void unpack8(const u32x4 w, float* f) { f[0] = bflo(w.x); f[1] = bfhi(w.x); f[2] = bflo(w.y); f[3] = bfhi(w.y); f[4] = bflo(w.z); f[5] = bfhi(w.z); f[6] = bflo(w.w); f[7] = bfhi(w.w); }
; #define SSD_LD(tt) ((live && (tt) >= 0) ? *(const u32x4*)(PJ + (size_t)tok_row(b, (tt)) * PW + C_XBC + xcol) : (u32x4){0u, 0u, 0u, 0u})
; template <bool PASSA> __device__ __forceinline__ void ssd_stage(const Ptrs& P, int l, int b, int ch, int gg, unsigned char* lds, int tid) {
;     ...
;         { const u32x4 h0 = SSD_LD(t0 - 3), h1 = SSD_LD(t0 - 2), h2 = SSD_LD(t0 - 1); unpack8(h0, x0); unpack8(h1, x1); unpack8(h2, x2); }
;         u32x4 n0 = SSD_LD(t0), n1 = SSD_LD(t0 + 1), n2 = SSD_LD(t0 + 2), n3 = SSD_LD(t0 + 3);
; #pragma unroll 1
;         for (int i = 0; i < 16; ++i) {
;             const int li = l0 + i;
;             unpack8(n0, x3); n0 = n1; n1 = n2; n2 = n3; n3 = (i + 4 < 16) ? SSD_LD(t0 + i + 4) : (u32x4){0u, 0u, 0u, 0u};
;             float o[8];
; #pragma unroll
;             for (int e = 0; e < 8; ++e) { float v = bias[e] + wgt[0][e] * x0[e] + wgt[1][e] * x1[e] + wgt[2][e] * x2[e] + wgt[3][e] * x3[e]; v = siluf(v); o[e] = (li < nvalid) ? v : 0.f;
;                 x0[e] = x1[e]; x1[e] = x2[e]; x2[e] = x3[e]; }
;             if (kind == 0) {
; #pragma unroll
;                 for (int e = 0; e < 8; ++e) Xt[sdz(i0 + e, li)] = (bf16_t)f2bf(o[e]);
;     ...
;     { const int hh = tid >> 7, li = tid & 127; const int h = gg * 4 + hh; float dt = 0.f, dA = 0.f;
;       if (li < nvalid) { const int row = (ch == 0) ? (MMAIN + b * NMETA + li) : (b * SEQ + 128 * (ch - 1) + li);
;           const float* dtraw = (const float*)((const unsigned char*)P.out + DO_DTRAW);
;           const float raw = dtraw[(size_t)row * 16 + h] + P.ssd_dt_bias[l * 16 + h];
.LBB0_924:
	s_or_b64 exec, exec, s[6:7]
	v_add_u32_e32 v17, 1, v88
	v_and_b32_e32 v111, 0x78, v17
	v_add_u32_e32 v17, 2, v88
	v_and_b32_e32 v113, 0x78, v17
	v_add_u32_e32 v17, 3, v88
	s_lshl_b32 s18, s13, 4
	v_and_b32_e32 v115, 0x78, v17
	v_add_u32_e32 v17, 4, v88
	v_and_b32_e32 v117, 0x78, v17
	v_add_u32_e32 v17, 5, v88
	s_add_i32 s6, s17, s18
	v_and_b32_e32 v119, 0x78, v17
	v_add_u32_e32 v17, 6, v88
	s_add_i32 s6, s6, 0x8004
	s_lshl_b32 s15, s13, 14
	v_and_b32_e32 v121, 0x78, v17
	v_add_u32_e32 v17, 7, v88
	v_add_u32_e32 v125, s6, v107
	s_movk_i32 s6, 0x1100
	s_waitcnt vmcnt(0)
	v_lshlrev_b32_e32 v102, 16, v64
	v_and_b32_e32 v103, 0xffff0000, v64
	v_mad_i32_i24 v110, v88, s26, 0
	v_and_b32_e32 v123, 0x78, v17
	s_add_i32 s17, s17, s15
	v_mul_lo_u32 v17, v106, s6
	v_lshlrev_b32_e32 v64, 1, v88
	v_readlane_b32 s6, v255, 25
	v_lshlrev_b32_e32 v82, 16, v72
	v_and_b32_e32 v83, 0xffff0000, v72
	v_lshlrev_b32_e32 v18, 16, v76
	v_and_b32_e32 v19, 0xffff0000, v76
	v_lshlrev_b32_e32 v100, 16, v65
	v_and_b32_e32 v101, 0xffff0000, v65
	v_lshlrev_b32_e32 v72, 16, v73
	v_and_b32_e32 v73, 0xffff0000, v73
	v_lshlrev_b32_e32 v84, 16, v77
	v_and_b32_e32 v85, 0xffff0000, v77
	v_lshlrev_b32_e32 v98, 16, v66
	v_and_b32_e32 v99, 0xffff0000, v66
	v_lshlrev_b32_e32 v76, 16, v74
	v_and_b32_e32 v77, 0xffff0000, v74
	v_lshlrev_b32_e32 v86, 16, v78
	v_and_b32_e32 v87, 0xffff0000, v78
	v_lshlrev_b32_e32 v96, 16, v67
	v_and_b32_e32 v97, 0xffff0000, v67
	v_lshlrev_b32_e32 v74, 16, v75
	v_and_b32_e32 v75, 0xffff0000, v75
	v_lshlrev_b32_e32 v78, 16, v79
	v_and_b32_e32 v79, 0xffff0000, v79
	v_and_b32_e32 v109, 0x78, v88
	v_add_u32_e32 v112, 0x110, v110
	v_add_u32_e32 v114, 0x220, v110
	v_add_u32_e32 v116, 0x330, v110
	v_add_u32_e32 v118, 0x440, v110
	v_add_u32_e32 v120, 0x550, v110
	v_add_u32_e32 v122, 0x660, v110
	v_add_u32_e32 v124, 0x770, v110
	v_add3_u32 v126, s17, -12, v107
	v_add3_u32 v127, v17, v64, s6
	s_mov_b32 s17, 0
	v_and_b32_e32 v132, 0x7f, v211
	s_add_i32 s100, s18, 0x8000
	s_add_i32 s101, s10, s15
	s_addk_i32 s101, 0xff80
	v_add_u32_e32 v136, s100, v132
	v_or_b32_e32 v133, s101, v132
	v_cndmask_b32_e64 v136, v136, v133, s[40:41]
	v_ashrrev_i32_e32 v138, 7, v211
	v_ashrrev_i32_e32 v137, 31, v136
	v_lshl_add_u32 v138, s3, 2, v138
	v_lshlrev_b64 v[136:137], 6, v[136:137]
	v_ashrrev_i32_e32 v139, 31, v138
	v_lshl_add_u64 v[136:137], v[170:171], 0, v[136:137]
	v_lshl_add_u64 v[136:137], v[138:139], 2, v[136:137]
	v_add_u32_e32 v138, s12, v138
	v_ashrrev_i32_e32 v139, 31, v138
	global_load_dword v129, v[136:137], off
	v_lshl_add_u64 v[136:137], v[138:139], 2, v[4:5]
	global_load_dword v134, v[136:137], off
	v_lshl_add_u64 v[136:137], v[138:139], 2, v[6:7]
	global_load_dword v135, v[136:137], off
	s_branch .Lsb_top_0

; template <bool PASSA> __device__ __forceinline__ void ssd_stage(const Ptrs& P, int l, int b, int ch, int gg, unsigned char* lds, int tid) {
;     ...
;     { const int hh = tid >> 7, li = tid & 127; const int h = gg * 4 + hh; float dt = 0.f, dA = 0.f;
;       if (li < nvalid) { const int row = (ch == 0) ? (MMAIN + b * NMETA + li) : (b * SEQ + 128 * (ch - 1) + li);
;           const float* dtraw = (const float*)((const unsigned char*)P.out + DO_DTRAW);
;           const float raw = dtraw[(size_t)row * 16 + h] + P.ssd_dt_bias[l * 16 + h];
;           dt = raw > 20.f ? raw : log1pf(__expf(raw)); dA = -dt * __expf(P.ssd_a_log[l * 16 + h]); }
;       DTS[hh * 128 + li] = dt; ACS[hh * 128 + li] = dA; }
.LBB0_938:
	v_and_b32_e32 v9, 0x7f, v211
	s_add_i32 s18, s18, 0x8000
	v_cmp_gt_u32_e32 vcc, s14, v9
	v_mov_b32_e32 v8, 0
	v_mov_b32_e32 v10, 0
	s_and_saveexec_b64 s[4:5], vcc
	s_cbranch_execz .LBB0_942
	s_add_i32 s6, s10, s15
	s_addk_i32 s6, 0xff80
	v_add_u32_e32 v10, s18, v9
	v_or_b32_e32 v9, s6, v9
	v_cndmask_b32_e64 v10, v10, v9, s[40:41]
	v_ashrrev_i32_e32 v8, 7, v211
	v_ashrrev_i32_e32 v11, 31, v10
	v_lshl_add_u32 v8, s3, 2, v8
	v_lshlrev_b64 v[10:11], 6, v[10:11]
	v_ashrrev_i32_e32 v9, 31, v8
	v_lshl_add_u64 v[10:11], v[170:171], 0, v[10:11]
	v_lshl_add_u64 v[10:11], v[8:9], 2, v[10:11]
	v_add_u32_e32 v8, s12, v8
	v_ashrrev_i32_e32 v9, 31, v8
	v_mov_b32_e32 v12, v129
	v_lshl_add_u64 v[10:11], v[8:9], 2, v[4:5]
	v_mov_b32_e32 v10, v134
	s_mov_b32 s6, 0x41a00000
	s_waitcnt vmcnt(0)
	v_add_f32_e32 v10, v12, v10
	v_cmp_nlt_f32_e32 vcc, s6, v10
	s_and_saveexec_b64 s[6:7], vcc
	s_cbranch_execz .LBB0_941
	v_mul_f32_e32 v10, 0x3fb8aa3b, v10
	v_exp_f32_e32 v17, v10
	s_mov_b32 s8, 0x3f2aaaab
	v_add_f32_e32 v12, 1.0, v17
	v_frexp_mant_f32_e32 v14, v12
	v_cvt_f64_f32_e32 v[10:11], v12
	v_frexp_exp_i32_f64_e32 v10, v[10:11]
	v_cmp_gt_f32_e32 vcc, s8, v14
	v_add_f32_e32 v13, -1.0, v12
	v_sub_f32_e32 v15, v13, v12
	v_subbrev_co_u32_e32 v20, vcc, 0, v10, vcc
	v_sub_u32_e32 v10, 0, v20
	v_sub_f32_e32 v13, v17, v13
	v_add_f32_e32 v15, 1.0, v15
	v_ldexp_f32 v11, v12, v10
	v_add_f32_e32 v13, v13, v15
	v_add_f32_e32 v12, -1.0, v11
	v_add_f32_e32 v14, 1.0, v11
	v_ldexp_f32 v10, v13, v10
	v_add_f32_e32 v13, 1.0, v12
	v_add_f32_e32 v15, -1.0, v14
	v_sub_f32_e32 v13, v11, v13
	v_sub_f32_e32 v11, v11, v15
	v_add_f32_e32 v13, v10, v13
	v_add_f32_e32 v10, v10, v11
	v_add_f32_e32 v21, v14, v10
	v_rcp_f32_e32 v23, v21
	v_sub_f32_e32 v11, v21, v14
	v_sub_f32_e32 v22, v10, v11
	v_add_f32_e32 v11, v12, v13
	v_mul_f32_e32 v25, v11, v23
	v_sub_f32_e32 v10, v11, v12
	v_mul_f32_e32 v12, v21, v25
	v_fma_f32 v14, v25, v21, -v12
	v_fmac_f32_e32 v14, v25, v22
	v_sub_f32_e32 v24, v13, v10
	v_add_f32_e32 v10, v12, v14
	v_sub_f32_e32 v13, v11, v10
	v_pk_add_f32 v[18:19], v[10:11], v[12:13] neg_lo:[0,1] neg_hi:[0,1]
	v_mov_b32_e32 v15, v10
	v_pk_add_f32 v[10:11], v[18:19], v[14:15] neg_lo:[0,1] neg_hi:[0,1]
	s_mov_b32 s8, 0x3f317218
	v_add_f32_e32 v11, v24, v11
	v_add_f32_e32 v10, v10, v11
	v_add_f32_e32 v11, v13, v10
	v_mul_f32_e32 v24, v23, v11
	v_mul_f32_e32 v12, v21, v24
	v_fma_f32 v14, v24, v21, -v12
	v_fmac_f32_e32 v14, v24, v22
	v_sub_f32_e32 v13, v13, v11
	v_add_f32_e32 v21, v10, v13
	v_add_f32_e32 v10, v12, v14
	v_sub_f32_e32 v13, v11, v10
	v_pk_add_f32 v[18:19], v[10:11], v[12:13] neg_lo:[0,1] neg_hi:[0,1]
	v_mov_b32_e32 v15, v10
	v_pk_add_f32 v[10:11], v[18:19], v[14:15] neg_lo:[0,1] neg_hi:[0,1]
	s_nop 0
	v_add_f32_e32 v11, v21, v11
	v_add_f32_e32 v10, v10, v11
	v_add_f32_e32 v11, v25, v24
	v_add_f32_e32 v10, v13, v10
	v_sub_f32_e32 v12, v11, v25
	v_mul_f32_e32 v10, v23, v10
	v_sub_f32_e32 v12, v24, v12
	v_add_f32_e32 v12, v12, v10
	v_add_f32_e32 v14, v11, v12
	v_mul_f32_e32 v15, v14, v14
	v_fmamk_f32 v10, v15, 0x3e9b6dac, v238
	v_fmaak_f32 v195, v15, v10, 0x3f2aaada
	v_cvt_f32_i32_e32 v10, v20
	v_sub_f32_e32 v11, v14, v11
	v_sub_f32_e32 v11, v12, v11
	v_ldexp_f32 v18, v11, 1
	v_mul_f32_e32 v11, v14, v15
	v_ldexp_f32 v13, v14, 1
	v_pk_mul_f32 v[14:15], v[10:11], v[194:195]
	s_nop 0
	v_fma_f32 v12, v10, s8, -v14
	v_fmac_f32_e32 v12, 0xb102e308, v10
	v_pk_add_f32 v[10:11], v[14:15], v[12:13]
	s_mov_b32 s8, 0x7f800000
	v_sub_f32_e32 v13, v11, v13
	v_sub_f32_e32 v13, v15, v13
	v_add_f32_e32 v19, v18, v13
	v_mov_b32_e32 v18, v14
	v_pk_add_f32 v[14:15], v[10:11], v[14:15] neg_lo:[0,1] neg_hi:[0,1]
	v_pk_add_f32 v[20:21], v[10:11], v[18:19]
	v_mov_b32_e32 v13, v10
	v_mov_b32_e32 v15, v21
	v_pk_add_f32 v[22:23], v[12:13], v[14:15] neg_lo:[0,1] neg_hi:[0,1]
	v_pk_add_f32 v[12:13], v[12:13], v[14:15]
	v_mov_b32_e32 v18, v19
	v_pk_add_f32 v[14:15], v[12:13], v[10:11] op_sel:[1,0] op_sel_hi:[0,1] neg_lo:[0,1] neg_hi:[0,1]
	v_pk_add_f32 v[24:25], v[20:21], v[14:15] op_sel_hi:[1,0] neg_lo:[0,1] neg_hi:[0,1]
	v_mov_b32_e32 v20, v21
	v_mov_b32_e32 v21, v13
	v_pk_mov_b32 v[14:15], v[10:11], v[14:15] op_sel:[1,0]
	v_mov_b32_e32 v19, v10
	v_pk_add_f32 v[14:15], v[20:21], v[14:15] neg_lo:[0,1] neg_hi:[0,1]
	v_mov_b32_e32 v24, v22
	v_pk_add_f32 v[10:11], v[18:19], v[14:15] neg_lo:[0,1] neg_hi:[0,1]
	v_mov_b32_e32 v23, v13
	v_pk_add_f32 v[14:15], v[24:25], v[10:11]
	v_cmp_neq_f32_e32 vcc, s8, v17
	v_pk_add_f32 v[18:19], v[14:15], v[14:15] op_sel:[0,1] op_sel_hi:[1,0]
	s_mov_b32 s8, 0x33800000
	v_pk_add_f32 v[12:13], v[12:13], v[18:19] op_sel:[1,0] op_sel_hi:[0,1]
	v_mov_b32_e32 v15, v12
	v_pk_add_f32 v[20:21], v[14:15], v[22:23] neg_lo:[0,1] neg_hi:[0,1]
	v_mov_b32_e32 v11, v18
	v_sub_f32_e32 v13, v14, v20
	v_pk_add_f32 v[10:11], v[10:11], v[20:21] neg_lo:[0,1] neg_hi:[0,1]
	v_sub_f32_e32 v13, v22, v13
	v_add_f32_e32 v10, v10, v13
	v_add_f32_e32 v10, v10, v11
	v_add_f32_e32 v10, v12, v10
	v_cndmask_b32_e32 v10, v237, v10, vcc
	v_cmp_ngt_f32_e32 vcc, -1.0, v17
	s_nop 1
	v_cndmask_b32_e32 v10, v243, v10, vcc
	v_cmp_neq_f32_e32 vcc, -1.0, v17
	s_nop 1
	v_cndmask_b32_e32 v10, v240, v10, vcc
	v_cmp_lt_f32_e64 vcc, |v17|, s8
	s_nop 1
	v_cndmask_b32_e32 v10, v10, v17, vcc
.LBB0_941:
	s_or_b64 exec, exec, s[6:7]
	v_mov_b32_e32 v8, v135
	s_waitcnt vmcnt(0)
	v_mul_f32_e32 v8, 0x3fb8aa3b, v8
	v_exp_f32_e32 v8, v8
	s_nop 0
	v_mul_f32_e64 v8, v8, -v10
